# v43 + outpost per-token loop: all 16 row loads of the two tokens issued up front with counted waits
# speedup vs baseline: 1.0050x; 1.0050x over previous
; __device__ __forceinline__ void unpack8(u32x4 w, float* f) { f[0] = bflo(w.x); f[1] = bfhi(w.x); f[2] = bflo(w.y); f[3] = bfhi(w.y); f[4] = bflo(w.z); f[5] = bfhi(w.z); f[6] = bflo(w.w); f[7] = bfhi(w.w); }
; __device__ void outpost_phase(const Params& P, int l, unsigned char* smem) {
;     ...
;         const int tl = 8 * w + ti; const int tok = (int)tok0 + tl;
;         const size_t off = (size_t)tok * 512 + c0;
;         float r[8], v[8], kf[8], kb[8], kx[8], gt[8], y[8], o[8];
;         { const f32x4 y0 = *(const f32x4*)(Yb + tl * 512 + c0), y1 = *(const f32x4*)(Yb + tl * 512 + c0 + 4); y[0] = y0[0]; y[1] = y0[1]; y[2] = y0[2]; y[3] = y0[3]; y[4] = y1[0]; y[5] = y1[1]; y[6] = y1[2]; y[7] = y1[3]; }
;         unpack8(*(const u32x4*)(R + off), r); unpack8(*(const u32x4*)(V + off), v);
;         unpack8(*(const u32x4*)(AF + off), kf); unpack8(*(const u32x4*)(AB + off), kb); unpack8(*(const u32x4*)(Kb + off), kx); unpack8(*(const u32x4*)(GATE + off), gt);
;         float sm = 0.f, bs = 0.f;
; #pragma unroll
;         for (int j = 0; j < 8; ++j) { sm += y[j]; bs += r[j] * kx[j] * (2.0f + (kf[j] + kb[j] - 2.0f) * (j < 4 ? ka0[j] : ka1[j - 4])) * (j < 4 ? rk0[j] : rk1[j - 4]); }
;         sm += __shfl_xor(sm, 1); sm += __shfl_xor(sm, 2); sm += __shfl_xor(sm, 4); bs += __shfl_xor(bs, 1); bs += __shfl_xor(bs, 2); bs += __shfl_xor(bs, 4);
.LBB0_110:
	v_lshl_add_u64 v[12:13], s[6:7], 0, v[164:165]
	v_add_co_u32_e32 v4, vcc, 0xe600000, v12
	v_add_u32_e32 v14, s0, v197
	s_nop 0
	v_addc_co_u32_e32 v5, vcc, 0, v13, vcc
	v_add_co_u32_e32 v6, vcc, 0x10600000, v12
	ds_read_b128 v[0:3], v14
	ds_read_b128 v[18:21], v14 offset:16
	v_addc_co_u32_e32 v7, vcc, 0, v13, vcc
	v_add_co_u32_e32 v8, vcc, 0x12600000, v12
	global_load_dwordx4 v[96:99], v[4:5], off
	global_load_dwordx4 v[100:103], v[6:7], off
	v_addc_co_u32_e32 v9, vcc, 0, v13, vcc
	v_add_co_u32_e32 v10, vcc, 0x13600000, v12
	global_load_dwordx4 v[104:107], v[8:9], off
	s_nop 0
	v_addc_co_u32_e32 v11, vcc, 0, v13, vcc
	global_load_dwordx4 v[108:111], v[10:11], off
	v_add_co_u32_e32 v16, vcc, 0xf600000, v12
	s_waitcnt lgkmcnt(1)
	v_add_f32_e32 v15, 0, v0
	v_addc_co_u32_e32 v17, vcc, 0, v13, vcc
	global_load_dwordx4 v[116:119], v[16:17], off
	v_add_co_u32_e32 v78, vcc, 0x14600000, v12
	v_add_f32_e32 v15, v1, v15
	s_nop 0
	v_addc_co_u32_e32 v79, vcc, 0, v13, vcc
	global_load_dwordx4 v[120:123], v[78:79], off
	v_add_co_u32_e32 v114, vcc, 0x19600000, v12
	s_nop 1
	v_addc_co_u32_e32 v115, vcc, 0, v13, vcc
	v_add_co_u32_e32 v198, vcc, 0x1a600000, v12
	s_nop 1
	v_addc_co_u32_e32 v199, vcc, 0, v13, vcc
	global_load_dwordx4 v[124:127], v[114:115], off
	global_load_dwordx4 v[128:131], v[198:199], off
	global_load_dwordx4 v[132:135], v[4:5], off offset:1024
	global_load_dwordx4 v[136:139], v[6:7], off offset:1024
	global_load_dwordx4 v[140:143], v[8:9], off offset:1024
	global_load_dwordx4 v[200:203], v[10:11], off offset:1024
	global_load_dwordx4 v[204:207], v[16:17], off offset:1024
	global_load_dwordx4 v[208:211], v[78:79], off offset:1024
	global_load_dwordx4 v[212:215], v[114:115], off offset:1024
	global_load_dwordx4 v[216:219], v[198:199], off offset:1024
	v_add_f32_e32 v15, v2, v15
	v_add_f32_e32 v15, v3, v15
	s_waitcnt lgkmcnt(0)
	v_add_f32_e32 v15, v18, v15
	v_add_f32_e32 v15, v19, v15
	v_add_f32_e32 v15, v20, v15
	v_add_f32_e32 v15, v21, v15
	s_mov_b32 s1, 0x19600000
	s_addk_i32 s0, 0x1000
	s_waitcnt vmcnt(15)
	v_and_b32_e32 v31, 0xffff0000, v96
	v_lshlrev_b32_e32 v30, 16, v96
	s_waitcnt vmcnt(13)
	v_and_b32_e32 v77, 0xffff0000, v104
	v_lshlrev_b32_e32 v76, 16, v104
	s_waitcnt vmcnt(12)
	v_and_b32_e32 v93, 0xffff0000, v108
	v_lshlrev_b32_e32 v92, 16, v108
	v_pk_add_f32 v[76:77], v[76:77], v[92:93]
	v_lshlrev_b32_e32 v72, 16, v109
	v_pk_add_f32 v[76:77], v[76:77], -2.0 op_sel_hi:[1,0]
	s_waitcnt vmcnt(11)
	v_and_b32_e32 v95, 0xffff0000, v116
	v_lshlrev_b32_e32 v94, 16, v116
	v_pk_mul_f32 v[30:31], v[30:31], v[94:95]
	v_pk_fma_f32 v[76:77], v[36:37], v[76:77], 2.0 op_sel_hi:[1,1,0]
	s_waitcnt vmcnt(10)
	v_lshlrev_b32_e32 v84, 16, v121
	v_pk_mul_f32 v[30:31], v[30:31], v[76:77]
	v_and_b32_e32 v77, 0xffff0000, v117
	v_pk_mul_f32 v[30:31], v[68:69], v[30:31]
	v_lshlrev_b32_e32 v76, 16, v117
	v_add_f32_e32 v22, 0, v30
	v_add_f32_e32 v80, v31, v22
	v_and_b32_e32 v31, 0xffff0000, v97
	v_lshlrev_b32_e32 v30, 16, v97
	v_and_b32_e32 v23, 0xffff0000, v105
	v_lshlrev_b32_e32 v22, 16, v105
	v_and_b32_e32 v73, 0xffff0000, v109
	v_pk_add_f32 v[22:23], v[22:23], v[72:73]
	v_pk_mul_f32 v[30:31], v[30:31], v[76:77]
	v_pk_add_f32 v[22:23], v[22:23], -2.0 op_sel_hi:[1,0]
	v_and_b32_e32 v73, 0xffff0000, v110
	v_pk_fma_f32 v[22:23], v[38:39], v[22:23], 2.0 op_sel_hi:[1,1,0]
	v_lshlrev_b32_e32 v72, 16, v110
	v_pk_mul_f32 v[22:23], v[30:31], v[22:23]
	v_and_b32_e32 v31, 0xffff0000, v106
	v_pk_mul_f32 v[22:23], v[70:71], v[22:23]
	v_lshlrev_b32_e32 v30, 16, v106
	v_add_f32_e32 v22, v22, v80
	v_pk_add_f32 v[30:31], v[30:31], v[72:73]
	v_add_f32_e32 v80, v23, v22
	v_and_b32_e32 v23, 0xffff0000, v98
	v_lshlrev_b32_e32 v22, 16, v98
	v_and_b32_e32 v77, 0xffff0000, v118
	v_lshlrev_b32_e32 v76, 16, v118
	v_pk_add_f32 v[30:31], v[30:31], -2.0 op_sel_hi:[1,0]
	v_pk_mul_f32 v[22:23], v[22:23], v[76:77]
	v_pk_fma_f32 v[30:31], v[32:33], v[30:31], 2.0 op_sel_hi:[1,1,0]
	v_lshlrev_b32_e32 v24, 16, v107
	v_pk_mul_f32 v[22:23], v[22:23], v[30:31]
	v_and_b32_e32 v31, 0xffff0000, v111
	v_pk_mul_f32 v[22:23], v[64:65], v[22:23]
	v_lshlrev_b32_e32 v30, 16, v111
	v_add_f32_e32 v22, v22, v80
	v_add_f32_e32 v74, v23, v22
	v_and_b32_e32 v23, 0xffff0000, v99
	v_lshlrev_b32_e32 v22, 16, v99
	v_and_b32_e32 v25, 0xffff0000, v107
	v_pk_add_f32 v[24:25], v[24:25], v[30:31]
	v_and_b32_e32 v73, 0xffff0000, v119
	v_lshlrev_b32_e32 v72, 16, v119
	v_pk_add_f32 v[24:25], v[24:25], -2.0 op_sel_hi:[1,0]
	v_pk_mul_f32 v[22:23], v[22:23], v[72:73]
	v_pk_fma_f32 v[24:25], v[34:35], v[24:25], 2.0 op_sel_hi:[1,1,0]
	v_lshlrev_b32_e32 v30, 16, v103
	v_pk_mul_f32 v[22:23], v[22:23], v[24:25]
	v_and_b32_e32 v31, 0xffff0000, v103
	v_pk_mul_f32 v[22:23], v[66:67], v[22:23]
	v_lshlrev_b32_e32 v72, 16, v123
	v_add_f32_e32 v22, v22, v74
	v_add_f32_e32 v22, v23, v22
	ds_bpermute_b32 v23, v179, v15
	v_and_b32_e32 v73, 0xffff0000, v123
	v_lshlrev_b32_e32 v76, 16, v102
	v_and_b32_e32 v77, 0xffff0000, v102
	v_lshlrev_b32_e32 v28, 16, v122
	s_waitcnt lgkmcnt(0)
	v_add_f32_e32 v15, v15, v23
	ds_bpermute_b32 v23, v178, v15
	v_and_b32_e32 v29, 0xffff0000, v122
	v_lshlrev_b32_e32 v82, 16, v101
	v_and_b32_e32 v83, 0xffff0000, v101
	v_lshlrev_b32_e32 v90, 16, v100
	s_waitcnt lgkmcnt(0)
	v_add_f32_e32 v15, v15, v23
	ds_bpermute_b32 v23, v161, v15
	v_and_b32_e32 v91, 0xffff0000, v100
	v_and_b32_e32 v85, 0xffff0000, v121
	v_lshlrev_b32_e32 v26, 16, v120
	v_and_b32_e32 v27, 0xffff0000, v120
	s_waitcnt lgkmcnt(0)
	v_add_f32_e32 v15, v15, v23
	ds_bpermute_b32 v23, v179, v22
	s_waitcnt lgkmcnt(0)
	v_add_f32_e32 v22, v22, v23
	ds_bpermute_b32 v23, v178, v22
	s_waitcnt lgkmcnt(0)
; __device__ __forceinline__ void unpack8(u32x4 w, float* f) { f[0] = bflo(w.x); f[1] = bfhi(w.x); f[2] = bflo(w.y); f[3] = bfhi(w.y); f[4] = bflo(w.z); f[5] = bfhi(w.z); f[6] = bflo(w.w); f[7] = bfhi(w.w); }
; __device__ __forceinline__ u32x4 pack8(const float* f) { u32x4 w; w.x = pk2(f[0], f[1]); w.y = pk2(f[2], f[3]); w.z = pk2(f[4], f[5]); w.w = pk2(f[6], f[7]); return w; }
; __device__ void outpost_phase(const Params& P, int l, unsigned char* smem) {
;     ...
;         const float mean = sm * (1.0f / 64.0f); float vs = 0.f;
; #pragma unroll
;         for (int j = 0; j < 8; ++j) { const float d = y[j] - mean; vs += d * d; }
;         vs += __shfl_xor(vs, 1); vs += __shfl_xor(vs, 2); vs += __shfl_xor(vs, 4);
;         const float rstd = rsqrtf(vs * (1.0f / 64.0f) + 64e-5f);
; #pragma unroll
;         for (int j = 0; j < 8; ++j) { const float g = j < 4 ? lg0[j] : lg1[j - 4], bb = j < 4 ? lb0[j] : lb1[j - 4]; o[j] = ((y[j] - mean) * rstd * g + bb + bs * v[j]) * gt[j]; }
;         *(u32x4*)(AO + (size_t)tok * 1024 + c0) = pack8(o);
;         float a0[8], a1[8], d[8]; unpack8(*(const u32x4*)(O0 + off), a0); unpack8(*(const u32x4*)(O1 + off), a1);
;         float sq = 0.f;
; #pragma unroll
;         for (int j = 0; j < 8; ++j) { d[j] = a0[j] - lam * a1[j]; sq += d[j] * d[j]; }
;         sq += __shfl_xor(sq, 1); sq += __shfl_xor(sq, 2); sq += __shfl_xor(sq, 4); sq += __shfl_xor(sq, 8);
;         const float rs = rsqrtf(sq * (1.0f / 128.0f) + 1e-6f) * (1.0f - lam_init);
; #pragma unroll
;         for (int j = 0; j < 8; ++j) d[j] *= rs * (j < 4 ? sg0[j] : sg1[j - 4]);
;         *(u32x4*)(AO + (size_t)tok * 1024 + 512 + c0) = pack8(d);
	v_add_f32_e32 v23, v22, v23
	ds_bpermute_b32 v24, v161, v23
	v_mul_f32_e32 v22, 0x3c800000, v15
	v_pk_add_f32 v[0:1], v[0:1], v[22:23] op_sel_hi:[1,0] neg_lo:[0,1] neg_hi:[0,1]
	v_pk_add_f32 v[20:21], v[20:21], v[22:23] op_sel_hi:[1,0] neg_lo:[0,1] neg_hi:[0,1]
	v_pk_add_f32 v[18:19], v[18:19], v[22:23] op_sel_hi:[1,0] neg_lo:[0,1] neg_hi:[0,1]
	s_waitcnt lgkmcnt(0)
	v_add_f32_e32 v24, v23, v24
	v_pk_add_f32 v[2:3], v[2:3], v[22:23] op_sel_hi:[1,0] neg_lo:[0,1] neg_hi:[0,1]
	v_pk_mul_f32 v[22:23], v[0:1], v[0:1]
	v_pk_mul_f32 v[86:87], v[2:3], v[2:3]
	v_add_f32_e32 v15, v22, v23
	v_add_f32_e32 v15, v86, v15
	v_pk_mul_f32 v[80:81], v[18:19], v[18:19]
	v_add_f32_e32 v15, v87, v15
	v_add_f32_e32 v15, v80, v15
	v_pk_mul_f32 v[74:75], v[20:21], v[20:21]
	v_add_f32_e32 v15, v81, v15
	v_add_f32_e32 v15, v74, v15
	v_add_f32_e32 v15, v75, v15
	ds_bpermute_b32 v22, v179, v15
	s_waitcnt lgkmcnt(0)
	v_add_f32_e32 v15, v15, v22
	ds_bpermute_b32 v22, v178, v15
	s_waitcnt lgkmcnt(0)
	v_add_f32_e32 v15, v15, v22
	ds_bpermute_b32 v22, v161, v15
	s_waitcnt lgkmcnt(0)
	v_add_f32_e32 v15, v15, v22
	v_fmamk_f32 v15, v15, 0x3c800000, v155
	v_cmp_gt_f32_e32 vcc, s73, v15
	v_mul_f32_e32 v22, 0x4b800000, v15
	s_nop 0
	v_cndmask_b32_e32 v15, v15, v22, vcc
	v_rsq_f32_e32 v15, v15
	s_nop 0
	v_mul_f32_e32 v22, 0x45800000, v15
	v_cndmask_b32_e32 v22, v15, v22, vcc
	v_pk_mul_f32 v[0:1], v[0:1], v[22:23] op_sel_hi:[1,0]
	v_pk_mul_f32 v[2:3], v[2:3], v[22:23] op_sel_hi:[1,0]
	v_pk_mul_f32 v[18:19], v[18:19], v[22:23] op_sel_hi:[1,0]
	v_pk_fma_f32 v[0:1], v[60:61], v[0:1], v[52:53]
	v_pk_fma_f32 v[2:3], v[62:63], v[2:3], v[54:55]
	v_pk_fma_f32 v[18:19], v[56:57], v[18:19], v[48:49]
	v_pk_fma_f32 v[0:1], v[24:25], v[90:91], v[0:1] op_sel_hi:[0,1,1]
	v_pk_fma_f32 v[2:3], v[24:25], v[82:83], v[2:3] op_sel_hi:[0,1,1]
	v_pk_fma_f32 v[18:19], v[24:25], v[76:77], v[18:19] op_sel_hi:[0,1,1]
	v_pk_mul_f32 v[20:21], v[20:21], v[22:23] op_sel_hi:[1,0]
	v_pk_mul_f32 v[0:1], v[0:1], v[26:27]
	v_pk_mul_f32 v[2:3], v[2:3], v[84:85]
	v_pk_mul_f32 v[18:19], v[18:19], v[28:29]
	v_pk_fma_f32 v[20:21], v[58:59], v[20:21], v[50:51]
	v_cvt_pk_bf16_f32 v0, v0, v1
	v_pk_fma_f32 v[20:21], v[24:25], v[30:31], v[20:21] op_sel_hi:[0,1,1]
	v_cvt_pk_bf16_f32 v1, v2, v3
	v_cvt_pk_bf16_f32 v2, v18, v19
	v_lshl_add_u64 v[18:19], s[4:5], 0, v[164:165]
	v_pk_mul_f32 v[20:21], v[20:21], v[72:73]
	v_add_co_u32_e32 v72, vcc, s33, v18
	v_cvt_pk_bf16_f32 v3, v20, v21
	s_nop 0
	v_addc_co_u32_e32 v73, vcc, 0, v19, vcc
	v_add_co_u32_e32 v74, vcc, s1, v12
	s_mov_b32 s1, 0x1a600000
	s_nop 0
	v_addc_co_u32_e32 v75, vcc, 0, v13, vcc
	v_add_co_u32_e32 v76, vcc, s1, v12
	global_store_dwordx4 v[72:73], v[0:3], off
	s_nop 0
	v_addc_co_u32_e32 v77, vcc, 0, v13, vcc
	s_add_u32 s4, s4, 0x1000
	s_addc_u32 s5, s5, 0
	s_add_u32 s6, s6, 0x800
	s_addc_u32 s7, s7, 0
	s_cmpk_eq_i32 s0, 0x4000
	s_waitcnt vmcnt(10)
	v_lshlrev_b32_e32 v12, 16, v127
	v_and_b32_e32 v13, 0xffff0000, v127
	v_lshlrev_b32_e32 v24, 16, v126
	v_and_b32_e32 v25, 0xffff0000, v126
	s_waitcnt vmcnt(9)
	v_lshlrev_b32_e32 v2, 16, v130
	v_and_b32_e32 v3, 0xffff0000, v130
	v_pk_fma_f32 v[2:3], v[148:149], v[2:3], v[24:25] neg_lo:[1,0,0] neg_hi:[1,0,0]
	v_lshlrev_b32_e32 v24, 16, v125
	v_and_b32_e32 v25, 0xffff0000, v125
	v_lshlrev_b32_e32 v28, 16, v124
	v_and_b32_e32 v29, 0xffff0000, v124
	v_lshlrev_b32_e32 v0, 16, v128
	v_and_b32_e32 v1, 0xffff0000, v128
	v_lshlrev_b32_e32 v26, 16, v129
	v_and_b32_e32 v27, 0xffff0000, v129
	v_pk_fma_f32 v[0:1], v[148:149], v[0:1], v[28:29] neg_lo:[1,0,0] neg_hi:[1,0,0]
	v_pk_fma_f32 v[24:25], v[148:149], v[26:27], v[24:25] neg_lo:[1,0,0] neg_hi:[1,0,0]
	v_pk_mul_f32 v[18:19], v[0:1], v[0:1]
	v_pk_mul_f32 v[26:27], v[24:25], v[24:25]
	v_add_f32_e32 v15, v18, v19
	v_add_f32_e32 v15, v26, v15
	v_lshlrev_b32_e32 v22, 16, v131
	v_and_b32_e32 v23, 0xffff0000, v131
	v_pk_mul_f32 v[20:21], v[2:3], v[2:3]
	v_add_f32_e32 v15, v27, v15
	v_pk_fma_f32 v[12:13], v[148:149], v[22:23], v[12:13] neg_lo:[1,0,0] neg_hi:[1,0,0]
	v_add_f32_e32 v15, v20, v15
	v_pk_mul_f32 v[22:23], v[12:13], v[12:13]
	v_add_f32_e32 v15, v21, v15
	v_add_f32_e32 v15, v22, v15
	v_add_f32_e32 v15, v23, v15
	ds_bpermute_b32 v18, v179, v15
	s_waitcnt lgkmcnt(0)
	v_add_f32_e32 v15, v15, v18
	ds_bpermute_b32 v18, v178, v15
	s_waitcnt lgkmcnt(0)
	v_add_f32_e32 v15, v15, v18
	ds_bpermute_b32 v18, v161, v15
	s_waitcnt lgkmcnt(0)
	v_add_f32_e32 v15, v15, v18
	ds_bpermute_b32 v18, v147, v15
	s_waitcnt lgkmcnt(0)
	v_add_f32_e32 v15, v15, v18
	v_fmamk_f32 v15, v15, 0x3c000000, v156
	v_cmp_gt_f32_e32 vcc, s73, v15
	v_mul_f32_e32 v18, 0x4b800000, v15
	s_nop 0
	v_cndmask_b32_e32 v15, v15, v18, vcc
	v_rsq_f32_e32 v15, v15
	s_nop 0
	v_mul_f32_e32 v18, 0x45800000, v15
	v_cndmask_b32_e32 v15, v15, v18, vcc
	v_mul_f32_e32 v18, v180, v15
	v_pk_mul_f32 v[20:21], v[44:45], v[18:19] op_sel_hi:[1,0]
	v_pk_mul_f32 v[22:23], v[40:41], v[18:19] op_sel_hi:[1,0]
	v_pk_mul_f32 v[0:1], v[0:1], v[20:21]
	v_pk_mul_f32 v[20:21], v[46:47], v[18:19] op_sel_hi:[1,0]
	v_pk_mul_f32 v[18:19], v[42:43], v[18:19] op_sel_hi:[1,0]
	v_pk_mul_f32 v[20:21], v[24:25], v[20:21]
	v_pk_mul_f32 v[2:3], v[2:3], v[22:23]
	v_pk_mul_f32 v[12:13], v[12:13], v[18:19]
	v_cvt_pk_bf16_f32 v0, v0, v1
	v_cvt_pk_bf16_f32 v1, v20, v21
	v_cvt_pk_bf16_f32 v2, v2, v3
	v_cvt_pk_bf16_f32 v3, v12, v13
	global_store_dwordx4 v[72:73], v[0:3], off offset:1024
	ds_read_b128 v[0:3], v14 offset:2048
	ds_read_b128 v[12:15], v14 offset:2064
	s_nop 0
	s_nop 0
	s_nop 0
	s_nop 0
	s_waitcnt lgkmcnt(1)
	v_add_f32_e32 v78, 0, v0
	v_add_f32_e32 v86, v1, v78
	s_waitcnt vmcnt(9)
	v_and_b32_e32 v79, 0xffff0000, v132
	v_lshlrev_b32_e32 v78, 16, v132
	s_waitcnt vmcnt(7)
; __device__ __forceinline__ void unpack8(u32x4 w, float* f) { f[0] = bflo(w.x); f[1] = bfhi(w.x); f[2] = bflo(w.y); f[3] = bfhi(w.y); f[4] = bflo(w.z); f[5] = bfhi(w.z); f[6] = bflo(w.w); f[7] = bfhi(w.w); }
; __device__ void outpost_phase(const Params& P, int l, unsigned char* smem) {
;     ...
;         { const f32x4 y0 = *(const f32x4*)(Yb + tl * 512 + c0), y1 = *(const f32x4*)(Yb + tl * 512 + c0 + 4); y[0] = y0[0]; y[1] = y0[1]; y[2] = y0[2]; y[3] = y0[3]; y[4] = y1[0]; y[5] = y1[1]; y[6] = y1[2]; y[7] = y1[3]; }
;         unpack8(*(const u32x4*)(R + off), r); unpack8(*(const u32x4*)(V + off), v);
;         unpack8(*(const u32x4*)(AF + off), kf); unpack8(*(const u32x4*)(AB + off), kb); unpack8(*(const u32x4*)(Kb + off), kx); unpack8(*(const u32x4*)(GATE + off), gt);
;         float sm = 0.f, bs = 0.f;
; #pragma unroll
;         for (int j = 0; j < 8; ++j) { sm += y[j]; bs += r[j] * kx[j] * (2.0f + (kf[j] + kb[j] - 2.0f) * (j < 4 ? ka0[j] : ka1[j - 4])) * (j < 4 ? rk0[j] : rk1[j - 4]); }
;         sm += __shfl_xor(sm, 1); sm += __shfl_xor(sm, 2); sm += __shfl_xor(sm, 4); bs += __shfl_xor(bs, 1); bs += __shfl_xor(bs, 2); bs += __shfl_xor(bs, 4);
;         const float mean = sm * (1.0f / 64.0f); float vs = 0.f;
; #pragma unroll
;         for (int j = 0; j < 8; ++j) { const float d = y[j] - mean; vs += d * d; }
;         vs += __shfl_xor(vs, 1); vs += __shfl_xor(vs, 2); vs += __shfl_xor(vs, 4);
	v_and_b32_e32 v81, 0xffff0000, v140
	v_lshlrev_b32_e32 v80, 16, v140
	s_waitcnt vmcnt(6)
	v_and_b32_e32 v83, 0xffff0000, v200
	v_lshlrev_b32_e32 v82, 16, v200
	v_pk_add_f32 v[80:81], v[80:81], v[82:83]
	s_waitcnt vmcnt(5)
	v_and_b32_e32 v85, 0xffff0000, v204
	v_lshlrev_b32_e32 v84, 16, v204
	v_pk_add_f32 v[80:81], v[80:81], -2.0 op_sel_hi:[1,0]
	v_pk_mul_f32 v[78:79], v[78:79], v[84:85]
	v_pk_fma_f32 v[80:81], v[36:37], v[80:81], 2.0 op_sel_hi:[1,1,0]
	v_lshlrev_b32_e32 v24, 16, v141
	v_pk_mul_f32 v[78:79], v[78:79], v[80:81]
	v_lshlrev_b32_e32 v28, 16, v201
	v_pk_mul_f32 v[78:79], v[68:69], v[78:79]
	v_lshlrev_b32_e32 v20, 16, v205
	v_add_f32_e32 v16, 0, v78
	v_add_f32_e32 v80, v79, v16
	v_add_f32_e32 v16, v2, v86
	v_and_b32_e32 v79, 0xffff0000, v133
	v_lshlrev_b32_e32 v78, 16, v133
	v_and_b32_e32 v25, 0xffff0000, v141
	v_and_b32_e32 v29, 0xffff0000, v201
	v_and_b32_e32 v21, 0xffff0000, v205
	v_add_f32_e32 v81, v3, v16
	v_pk_mul_f32 v[16:17], v[78:79], v[20:21]
	v_pk_add_f32 v[20:21], v[24:25], v[28:29]
	v_and_b32_e32 v25, 0xffff0000, v202
	v_pk_add_f32 v[20:21], v[20:21], -2.0 op_sel_hi:[1,0]
	v_lshlrev_b32_e32 v24, 16, v202
	v_pk_fma_f32 v[20:21], v[38:39], v[20:21], 2.0 op_sel_hi:[1,1,0]
	v_and_b32_e32 v29, 0xffff0000, v206
	v_pk_mul_f32 v[16:17], v[16:17], v[20:21]
	v_and_b32_e32 v21, 0xffff0000, v142
	v_pk_mul_f32 v[16:17], v[70:71], v[16:17]
	v_lshlrev_b32_e32 v20, 16, v142
	v_add_f32_e32 v16, v16, v80
	v_add_f32_e32 v78, v17, v16
	s_waitcnt lgkmcnt(0)
	v_add_f32_e32 v16, v12, v81
	v_pk_add_f32 v[20:21], v[20:21], v[24:25]
	v_add_f32_e32 v79, v13, v16
	v_and_b32_e32 v17, 0xffff0000, v134
	v_lshlrev_b32_e32 v16, 16, v134
	v_lshlrev_b32_e32 v28, 16, v206
	v_pk_add_f32 v[20:21], v[20:21], -2.0 op_sel_hi:[1,0]
	v_pk_mul_f32 v[16:17], v[16:17], v[28:29]
	v_pk_fma_f32 v[20:21], v[32:33], v[20:21], 2.0 op_sel_hi:[1,1,0]
	v_and_b32_e32 v25, 0xffff0000, v203
	v_pk_mul_f32 v[16:17], v[16:17], v[20:21]
	v_and_b32_e32 v21, 0xffff0000, v143
	v_pk_mul_f32 v[16:17], v[64:65], v[16:17]
	v_lshlrev_b32_e32 v20, 16, v143
	v_add_f32_e32 v16, v16, v78
	v_lshlrev_b32_e32 v24, 16, v203
	v_add_f32_e32 v26, v17, v16
	v_add_f32_e32 v16, v14, v79
	v_and_b32_e32 v23, 0xffff0000, v207
	v_lshlrev_b32_e32 v22, 16, v207
	v_pk_add_f32 v[18:19], v[20:21], v[24:25]
	v_add_f32_e32 v28, v15, v16
	v_and_b32_e32 v17, 0xffff0000, v135
	v_lshlrev_b32_e32 v16, 16, v135
	v_pk_add_f32 v[18:19], v[18:19], -2.0 op_sel_hi:[1,0]
	v_pk_mul_f32 v[16:17], v[16:17], v[22:23]
	v_pk_fma_f32 v[18:19], v[34:35], v[18:19], 2.0 op_sel_hi:[1,1,0]
	v_and_b32_e32 v29, 0xffff0000, v137
	v_pk_mul_f32 v[16:17], v[16:17], v[18:19]
	s_waitcnt vmcnt(4)
	v_lshlrev_b32_e32 v30, 16, v209
	v_pk_mul_f32 v[16:17], v[66:67], v[16:17]
	v_and_b32_e32 v31, 0xffff0000, v209
	v_add_f32_e32 v16, v16, v26
	v_add_f32_e32 v16, v17, v16
	ds_bpermute_b32 v17, v179, v28
	v_lshlrev_b32_e32 v80, 16, v136
	v_and_b32_e32 v81, 0xffff0000, v136
	v_lshlrev_b32_e32 v4, 16, v208
	v_lshlrev_b32_e32 v20, 16, v139
	s_waitcnt lgkmcnt(0)
	v_add_f32_e32 v17, v28, v17
	ds_bpermute_b32 v18, v178, v17
	v_lshlrev_b32_e32 v28, 16, v137
	v_and_b32_e32 v5, 0xffff0000, v208
	v_and_b32_e32 v21, 0xffff0000, v139
	v_lshlrev_b32_e32 v22, 16, v138
	s_waitcnt lgkmcnt(0)
	v_add_f32_e32 v17, v17, v18
	ds_bpermute_b32 v18, v161, v17
	v_and_b32_e32 v23, 0xffff0000, v138
	v_lshlrev_b32_e32 v6, 16, v210
	v_and_b32_e32 v7, 0xffff0000, v210
	s_waitcnt lgkmcnt(0)
	v_add_f32_e32 v17, v17, v18
	ds_bpermute_b32 v18, v179, v16
	v_mul_f32_e32 v24, 0x3c800000, v17
	v_pk_add_f32 v[0:1], v[0:1], v[24:25] op_sel_hi:[1,0] neg_lo:[0,1] neg_hi:[0,1]
	v_pk_add_f32 v[2:3], v[2:3], v[24:25] op_sel_hi:[1,0] neg_lo:[0,1] neg_hi:[0,1]
	v_pk_mul_f32 v[8:9], v[0:1], v[0:1]
	s_waitcnt lgkmcnt(0)
	v_add_f32_e32 v16, v16, v18
	ds_bpermute_b32 v18, v178, v16
	v_pk_mul_f32 v[78:79], v[2:3], v[2:3]
	v_add_f32_e32 v8, v8, v9
	v_and_b32_e32 v17, 0xffff0000, v211
	v_add_f32_e32 v8, v78, v8
	s_waitcnt lgkmcnt(0)
	v_add_f32_e32 v16, v16, v18
	ds_bpermute_b32 v18, v161, v16
	v_add_f32_e32 v8, v79, v8
	v_pk_add_f32 v[14:15], v[14:15], v[24:25] op_sel_hi:[1,0] neg_lo:[0,1] neg_hi:[0,1]
	s_waitcnt lgkmcnt(0)
; __device__ __forceinline__ void unpack8(u32x4 w, float* f) { f[0] = bflo(w.x); f[1] = bfhi(w.x); f[2] = bflo(w.y); f[3] = bfhi(w.y); f[4] = bflo(w.z); f[5] = bfhi(w.z); f[6] = bflo(w.w); f[7] = bfhi(w.w); }
; __device__ __forceinline__ u32x4 pack8(const float* f) { u32x4 w; w.x = pk2(f[0], f[1]); w.y = pk2(f[2], f[3]); w.z = pk2(f[4], f[5]); w.w = pk2(f[6], f[7]); return w; }
; __device__ void outpost_phase(const Params& P, int l, unsigned char* smem) {
;     ...
;         const float mean = sm * (1.0f / 64.0f); float vs = 0.f;
; #pragma unroll
;         for (int j = 0; j < 8; ++j) { const float d = y[j] - mean; vs += d * d; }
;         vs += __shfl_xor(vs, 1); vs += __shfl_xor(vs, 2); vs += __shfl_xor(vs, 4);
;         const float rstd = rsqrtf(vs * (1.0f / 64.0f) + 64e-5f);
; #pragma unroll
;         for (int j = 0; j < 8; ++j) { const float g = j < 4 ? lg0[j] : lg1[j - 4], bb = j < 4 ? lb0[j] : lb1[j - 4]; o[j] = ((y[j] - mean) * rstd * g + bb + bs * v[j]) * gt[j]; }
;         *(u32x4*)(AO + (size_t)tok * 1024 + c0) = pack8(o);
;         float a0[8], a1[8], d[8]; unpack8(*(const u32x4*)(O0 + off), a0); unpack8(*(const u32x4*)(O1 + off), a1);
;         float sq = 0.f;
; #pragma unroll
;         for (int j = 0; j < 8; ++j) { d[j] = a0[j] - lam * a1[j]; sq += d[j] * d[j]; }
;         sq += __shfl_xor(sq, 1); sq += __shfl_xor(sq, 2); sq += __shfl_xor(sq, 4); sq += __shfl_xor(sq, 8);
;         const float rs = rsqrtf(sq * (1.0f / 128.0f) + 1e-6f) * (1.0f - lam_init);
; #pragma unroll
;         for (int j = 0; j < 8; ++j) d[j] *= rs * (j < 4 ? sg0[j] : sg1[j - 4]);
;         *(u32x4*)(AO + (size_t)tok * 1024 + 512 + c0) = pack8(d);
;       }
;       __syncthreads();
	v_add_f32_e32 v18, v16, v18
	v_lshlrev_b32_e32 v16, 16, v211
	v_pk_add_f32 v[10:11], v[12:13], v[24:25] op_sel_hi:[1,0] neg_lo:[0,1] neg_hi:[0,1]
	v_pk_mul_f32 v[26:27], v[14:15], v[14:15]
	v_pk_mul_f32 v[12:13], v[10:11], v[10:11]
	s_nop 0
	v_add_f32_e32 v8, v12, v8
	v_add_f32_e32 v8, v13, v8
	v_add_f32_e32 v8, v26, v8
	v_add_f32_e32 v8, v27, v8
	ds_bpermute_b32 v9, v179, v8
	s_waitcnt lgkmcnt(0)
	v_add_f32_e32 v8, v8, v9
	ds_bpermute_b32 v9, v178, v8
	s_waitcnt lgkmcnt(0)
	v_add_f32_e32 v8, v8, v9
	ds_bpermute_b32 v9, v161, v8
	s_waitcnt lgkmcnt(0)
	v_add_f32_e32 v8, v8, v9
	v_fmamk_f32 v8, v8, 0x3c800000, v155
	v_cmp_gt_f32_e32 vcc, s73, v8
	v_mul_f32_e32 v9, 0x4b800000, v8
	s_nop 0
	v_cndmask_b32_e32 v8, v8, v9, vcc
	v_rsq_f32_e32 v8, v8
	s_nop 0
	v_mul_f32_e32 v9, 0x45800000, v8
	v_cndmask_b32_e32 v8, v8, v9, vcc
	v_pk_mul_f32 v[0:1], v[0:1], v[8:9] op_sel_hi:[1,0]
	v_pk_mul_f32 v[2:3], v[2:3], v[8:9] op_sel_hi:[1,0]
	v_pk_fma_f32 v[0:1], v[60:61], v[0:1], v[52:53]
	v_pk_fma_f32 v[2:3], v[62:63], v[2:3], v[54:55]
	v_pk_fma_f32 v[0:1], v[18:19], v[80:81], v[0:1] op_sel_hi:[0,1,1]
	v_pk_mul_f32 v[0:1], v[0:1], v[4:5]
	v_pk_mul_f32 v[4:5], v[10:11], v[8:9] op_sel_hi:[1,0]
	v_pk_fma_f32 v[2:3], v[18:19], v[28:29], v[2:3] op_sel_hi:[0,1,1]
	v_pk_fma_f32 v[4:5], v[56:57], v[4:5], v[48:49]
	v_pk_mul_f32 v[2:3], v[2:3], v[30:31]
	v_pk_fma_f32 v[4:5], v[18:19], v[22:23], v[4:5] op_sel_hi:[0,1,1]
	v_pk_mul_f32 v[4:5], v[4:5], v[6:7]
	v_pk_mul_f32 v[6:7], v[14:15], v[8:9] op_sel_hi:[1,0]
	v_cvt_pk_bf16_f32 v0, v0, v1
	v_pk_fma_f32 v[6:7], v[58:59], v[6:7], v[50:51]
	v_cvt_pk_bf16_f32 v1, v2, v3
	v_pk_fma_f32 v[6:7], v[18:19], v[20:21], v[6:7] op_sel_hi:[0,1,1]
	v_pk_mul_f32 v[6:7], v[6:7], v[16:17]
	v_cvt_pk_bf16_f32 v2, v4, v5
	v_cvt_pk_bf16_f32 v3, v6, v7
	global_store_dwordx4 v[72:73], v[0:3], off offset:2048
	s_nop 0
	s_waitcnt vmcnt(4)
	v_lshlrev_b32_e32 v8, 16, v215
	v_and_b32_e32 v9, 0xffff0000, v215
	v_lshlrev_b32_e32 v12, 16, v214
	v_and_b32_e32 v13, 0xffff0000, v214
	s_waitcnt vmcnt(3)
	v_lshlrev_b32_e32 v2, 16, v218
	v_and_b32_e32 v3, 0xffff0000, v218
	v_pk_fma_f32 v[2:3], v[148:149], v[2:3], v[12:13] neg_lo:[1,0,0] neg_hi:[1,0,0]
	v_lshlrev_b32_e32 v12, 16, v213
	v_and_b32_e32 v13, 0xffff0000, v213
	v_lshlrev_b32_e32 v16, 16, v212
	v_and_b32_e32 v17, 0xffff0000, v212
	v_lshlrev_b32_e32 v0, 16, v216
	v_and_b32_e32 v1, 0xffff0000, v216
	v_lshlrev_b32_e32 v14, 16, v217
	v_and_b32_e32 v15, 0xffff0000, v217
	v_pk_fma_f32 v[0:1], v[148:149], v[0:1], v[16:17] neg_lo:[1,0,0] neg_hi:[1,0,0]
	v_pk_fma_f32 v[12:13], v[148:149], v[14:15], v[12:13] neg_lo:[1,0,0] neg_hi:[1,0,0]
	v_pk_mul_f32 v[4:5], v[0:1], v[0:1]
	v_pk_mul_f32 v[14:15], v[12:13], v[12:13]
	v_add_f32_e32 v4, v4, v5
	v_add_f32_e32 v4, v14, v4
	v_lshlrev_b32_e32 v10, 16, v219
	v_and_b32_e32 v11, 0xffff0000, v219
	v_pk_mul_f32 v[6:7], v[2:3], v[2:3]
	v_add_f32_e32 v4, v15, v4
	v_pk_fma_f32 v[8:9], v[148:149], v[10:11], v[8:9] neg_lo:[1,0,0] neg_hi:[1,0,0]
	v_add_f32_e32 v4, v6, v4
	v_pk_mul_f32 v[10:11], v[8:9], v[8:9]
	v_add_f32_e32 v4, v7, v4
	v_add_f32_e32 v4, v10, v4
	v_add_f32_e32 v4, v11, v4
	ds_bpermute_b32 v5, v179, v4
	s_waitcnt lgkmcnt(0)
	v_add_f32_e32 v4, v4, v5
	ds_bpermute_b32 v5, v178, v4
	s_waitcnt lgkmcnt(0)
	v_add_f32_e32 v4, v4, v5
	ds_bpermute_b32 v5, v161, v4
	s_waitcnt lgkmcnt(0)
	v_add_f32_e32 v4, v4, v5
	ds_bpermute_b32 v5, v147, v4
	s_waitcnt lgkmcnt(0)
	v_add_f32_e32 v4, v4, v5
	v_fmamk_f32 v4, v4, 0x3c000000, v156
	v_cmp_gt_f32_e32 vcc, s73, v4
	v_mul_f32_e32 v5, 0x4b800000, v4
	s_nop 0
	v_cndmask_b32_e32 v4, v4, v5, vcc
	v_rsq_f32_e32 v4, v4
	s_nop 0
	v_mul_f32_e32 v5, 0x45800000, v4
	v_cndmask_b32_e32 v4, v4, v5, vcc
	v_mul_f32_e32 v4, v180, v4
	v_pk_mul_f32 v[6:7], v[44:45], v[4:5] op_sel_hi:[1,0]
	v_pk_mul_f32 v[10:11], v[40:41], v[4:5] op_sel_hi:[1,0]
	v_pk_mul_f32 v[0:1], v[0:1], v[6:7]
	v_pk_mul_f32 v[6:7], v[46:47], v[4:5] op_sel_hi:[1,0]
	v_pk_mul_f32 v[4:5], v[42:43], v[4:5] op_sel_hi:[1,0]
	v_pk_mul_f32 v[6:7], v[12:13], v[6:7]
	v_pk_mul_f32 v[2:3], v[2:3], v[10:11]
	v_pk_mul_f32 v[4:5], v[8:9], v[4:5]
	v_cvt_pk_bf16_f32 v0, v0, v1
	v_cvt_pk_bf16_f32 v1, v6, v7
	v_cvt_pk_bf16_f32 v2, v2, v3
	v_cvt_pk_bf16_f32 v3, v4, v5
	global_store_dwordx4 v[72:73], v[0:3], off offset:3072
	s_cbranch_scc0 .LBB0_110
	s_add_i32 s11, s11, s94
	s_add_i32 s8, s8, s94
	s_cmpk_gt_i32 s11, 0xff
	s_barrier
	s_cbranch_scc0 .LBB0_107
